# e12 plus residual+norm GEMM epilogues: the four row-sum slot loads of the cross-workgroup exchange issued together (were three serialized L2 round trips behind the spin)
# speedup vs baseline: 1.0016x; 1.0016x over previous
.LBB0_487:
	s_and_saveexec_b64 s[0:1], s[6:7]
	s_cbranch_execz .LBB0_489
	v_add_u32_e32 v4, s83, v2
	v_ashrrev_i32_e32 v5, 31, v4
	v_lshl_add_u64 v[4:5], v[4:5], 4, s[8:9]
	global_load_dword v3, v[4:5], off sc1
	global_load_dword v6, v[4:5], off offset:4 sc1
	global_load_dword v248, v[4:5], off offset:8 sc1
	s_nop 0
	global_load_dword v4, v[4:5], off offset:12 sc1
	v_lshl_add_u32 v2, v2, 2, 0
	v_add_u32_e32 v2, 0x22400, v2
	s_waitcnt vmcnt(3)
	v_add_f32_e32 v3, 0, v3
	s_waitcnt vmcnt(2)
	v_add_f32_e32 v3, v3, v6
	s_waitcnt vmcnt(1)
	v_add_f32_e32 v3, v3, v248
	s_waitcnt vmcnt(0)
	v_add_f32_e32 v3, v3, v4
	v_fmamk_f32 v3, v3, 0x3a800000, v244
	v_rsq_f32_e32 v3, v3
	ds_write_b32 v2, v3

.LBB0_551:
	s_and_saveexec_b64 s[0:1], s[6:7]
	s_cbranch_execz .LBB0_553
	v_add_u32_e32 v4, s86, v2
	v_ashrrev_i32_e32 v5, 31, v4
	v_lshl_add_u64 v[4:5], v[4:5], 4, s[8:9]
	global_load_dword v3, v[4:5], off sc1
	global_load_dword v6, v[4:5], off offset:4 sc1
	global_load_dword v248, v[4:5], off offset:8 sc1
	s_nop 0
	global_load_dword v4, v[4:5], off offset:12 sc1
	v_lshl_add_u32 v2, v2, 2, 0
	v_add_u32_e32 v2, 0x22400, v2
	s_waitcnt vmcnt(3)
	v_add_f32_e32 v3, 0, v3
	s_waitcnt vmcnt(2)
	v_add_f32_e32 v3, v3, v6
	s_waitcnt vmcnt(1)
	v_add_f32_e32 v3, v3, v248
	s_waitcnt vmcnt(0)
	v_add_f32_e32 v3, v3, v4
	v_fmamk_f32 v3, v3, 0x3a800000, v244
	v_rsq_f32_e32 v3, v3
	ds_write_b32 v2, v3

.LBB0_626:
	s_waitcnt vmcnt(0) lgkmcnt(0)
	s_barrier
	s_and_saveexec_b64 s[0:1], s[6:7]
	s_cbranch_execz .LBB0_628
	v_lshl_add_u64 v[2:3], v[2:3], 4, s[8:9]
	global_load_dword v5, v[2:3], off sc1
	global_load_dword v6, v[2:3], off offset:4 sc1
	global_load_dword v248, v[2:3], off offset:8 sc1
	s_nop 0
	global_load_dword v2, v[2:3], off offset:12 sc1
	v_lshl_add_u32 v3, v4, 2, 0
	v_add_u32_e32 v3, 0x22400, v3
	s_waitcnt vmcnt(3)
	v_add_f32_e32 v5, 0, v5
	s_waitcnt vmcnt(2)
	v_add_f32_e32 v5, v5, v6
	s_waitcnt vmcnt(1)
	v_add_f32_e32 v5, v5, v248
	s_waitcnt vmcnt(0)
	v_add_f32_e32 v2, v5, v2
	v_fmamk_f32 v2, v2, 0x3a800000, v244
	v_rsq_f32_e32 v2, v2
	ds_write_b32 v3, v2
